# GEMM K-loop back-edge rotation: next iteration's first-phase address/scalar setup computed before the loop-back barrier instead of after it
# speedup vs baseline: 1.0071x; 1.0033x over previous
; #define PG8_STAGE(bufoff, gbase, voff) do { _Pragma("unroll") for (int _i = 0; _i < 2; ++_i) \
;         __builtin_amdgcn_global_load_lds((const unsigned*)((const char*)(gbase) + (voff)[_i]), (LAS unsigned*)(lds + (bufoff) + ldsw + _i * 8192), 16, 0, 0); } while (0)
; #define PG8_LDA(dst, b, h) do { _Pragma("unroll") for (int m = 0; m < 4; ++m) _Pragma("unroll") for (int k = 0; k < 2; ++k) dst[m][k] = *(const LAS bf16x8*)(lds + PG8_SA(b, h) + aoff + m * 2048 + k * 1024); } while (0)
; #define PG8_LDB(dst, b, h) do { _Pragma("unroll") for (int n = 0; n < 2; ++n) _Pragma("unroll") for (int k = 0; k < 2; ++k) dst[n][k] = *(const LAS bf16x8*)(lds + PG8_SB(b, h) + boff + n * 2048 + k * 1024); } while (0)
; #define PG8_MMA(ai, bj, At, Bt) do { __builtin_amdgcn_s_setprio(1); _Pragma("unroll") for (int m = 0; m < 4; ++m) _Pragma("unroll") for (int n = 0; n < 2; ++n) _Pragma("unroll") for (int k = 0; k < 2; ++k) \
;         acc[ai][bj][m][n] = __builtin_amdgcn_mfma_f32_16x16x32_bf16(Bt[n][k], At[m][k], acc[ai][bj][m][n], 0, 0, 0); __builtin_amdgcn_s_setprio(0); } while (0)
; #define PG8_WAIT_L(n) asm volatile("s_waitcnt lgkmcnt(" #n ")" ::: "memory")
; #define PG8_BAR __builtin_amdgcn_s_barrier()
; #define PG8_SCHED __builtin_amdgcn_sched_barrier(0)
; template <class Epi>
; DI void gemm_phase(LAS unsigned char* lds, const Gemm g, const StaticOrder& S, const Epi& E) {
;     ...
;             PG8_LDB(B0, 0, 0); PG8_SCHED; PG8_LDA(At, 0, 0); PG8_STAGE(PG8_SA(1, 1), a1 + hstepA, voffA);
;             PG8_WAIT_L(8); PG8_BAR; PG8_WAIT_L(0); PG8_MMA(0, 0, At, B0); PG8_BAR; PG8_SCHED;
;             PG8_LDB(B1, 0, 1); PG8_STAGE(PG8_SB(0, 0), b2, voffB);
;             PG8_BAR; PG8_WAIT_L(0); PG8_MMA(0, 1, At, B1); PG8_BAR;
;             PG8_LDA(At, 0, 1); PG8_STAGE(PG8_SA(0, 0), a2, voffA);
;             PG8_BAR; PG8_WAIT_L(0); PG8_MMA(1, 0, At, B0); PG8_BAR; PG8_SCHED;
.LBB0_240:
	s_cmp_gt_i32 s70, 3
	s_cselect_b64 s[20:21], -1, 0
	s_and_b64 s[20:21], s[94:95], s[20:21]
	s_and_b64 s[20:21], s[20:21], exec
	s_cselect_b32 s11, 4, s86
	s_add_i32 s20, s11, -2
	s_add_u32 s21, s16, 0x100
	s_addc_u32 s44, s17, 0
	s_add_u32 s16, s18, 0x80
	s_addc_u32 s17, s19, 0
	s_mov_b32 s18, 0
	s_add_i32 s45, s18, 2
	s_add_u32 s37, s16, 0x80
	s_addc_u32 s19, s17, 0
	s_waitcnt lgkmcnt(0)
	s_add_i32 s46, 0, 0x10000
	v_add_u32_e32 v0, s46, v147
	ds_read_b128 v[130:133], v0
	ds_read_b128 v[148:151], v0 offset:1024
	ds_read_b128 v[152:155], v0 offset:2048
	ds_read_b128 v[156:159], v0 offset:3072
	s_cmp_eq_u32 s20, s18
	s_cselect_b32 s18, s12, s37
	s_cselect_b32 s19, s13, s19
	s_cselect_b32 s43, s15, s44
	s_cselect_b32 s42, s14, s21
	v_lshl_add_u64 v[204:205], s[16:17], 0, v[144:145]
	s_add_i32 m0, s89, 0xc000
	ds_read_b128 v[160:163], v186
	ds_read_b128 v[164:167], v186 offset:1024
	ds_read_b128 v[168:171], v186 offset:2048
	ds_read_b128 v[172:175], v186 offset:3072
	ds_read_b128 v[188:191], v186 offset:4096
	ds_read_b128 v[192:195], v186 offset:5120
	ds_read_b128 v[196:199], v186 offset:6144
	ds_read_b128 v[200:203], v186 offset:7168
	global_load_lds_dwordx4 v[204:205], off
	v_lshl_add_u64 v[204:205], s[16:17], 0, v[142:143]
	s_add_i32 m0, s89, 0xe000
	s_nop 0
	global_load_lds_dwordx4 v[204:205], off
	s_waitcnt lgkmcnt(8)
	s_barrier
	s_waitcnt lgkmcnt(0)
	s_setprio 1
	s_waitcnt lgkmcnt(0)
	v_mfma_f32_16x16x32_bf16 v[126:129], v[130:133], v[160:163], 0
	v_mfma_f32_16x16x32_bf16 v[122:125], v[152:155], v[160:163], 0
	v_mfma_f32_16x16x32_bf16 v[118:121], v[130:133], v[168:171], 0
	v_mfma_f32_16x16x32_bf16 v[114:117], v[152:155], v[168:171], 0
	v_mfma_f32_16x16x32_bf16 v[106:109], v[130:133], v[188:191], 0
	v_mfma_f32_16x16x32_bf16 v[98:101], v[152:155], v[188:191], 0
	v_mfma_f32_16x16x32_bf16 v[90:93], v[130:133], v[196:199], 0
	v_mfma_f32_16x16x32_bf16 v[82:85], v[152:155], v[196:199], 0
	v_mfma_f32_16x16x32_bf16 v[126:129], v[148:151], v[164:167], v[126:129]
	v_mfma_f32_16x16x32_bf16 v[122:125], v[156:159], v[164:167], v[122:125]
	v_mfma_f32_16x16x32_bf16 v[118:121], v[148:151], v[172:175], v[118:121]
	v_mfma_f32_16x16x32_bf16 v[114:117], v[156:159], v[172:175], v[114:117]
	v_mfma_f32_16x16x32_bf16 v[106:109], v[148:151], v[192:195], v[106:109]
	v_mfma_f32_16x16x32_bf16 v[98:101], v[156:159], v[192:195], v[98:101]
	v_mfma_f32_16x16x32_bf16 v[90:93], v[148:151], v[200:203], v[90:93]
	v_mfma_f32_16x16x32_bf16 v[82:85], v[156:159], v[200:203], v[82:85]
	s_setprio 0
	s_barrier
	s_add_i32 s37, 0, 0x14000
	s_add_i32 s46, s46, s88
	v_add_u32_e32 v0, s37, v147
	v_lshl_add_u64 v[220:221], s[42:43], 0, v[136:137]
	s_mov_b32 m0, s46
	ds_read_b128 v[204:207], v0
	ds_read_b128 v[208:211], v0 offset:1024
	ds_read_b128 v[212:215], v0 offset:2048
	ds_read_b128 v[216:219], v0 offset:3072
	global_load_lds_dwordx4 v[220:221], off
	v_lshl_add_u64 v[222:223], s[42:43], 0, v[140:141]
	s_add_i32 m0, s46, 0x2000
	s_nop 0
	global_load_lds_dwordx4 v[222:223], off
	s_barrier
	s_waitcnt lgkmcnt(0)
	s_setprio 1
	s_waitcnt lgkmcnt(0)
	v_mfma_f32_16x16x32_bf16 v[110:113], v[204:207], v[160:163], 0
	v_mfma_f32_16x16x32_bf16 v[102:105], v[212:215], v[160:163], 0
	v_mfma_f32_16x16x32_bf16 v[94:97], v[204:207], v[168:171], 0
	v_mfma_f32_16x16x32_bf16 v[86:89], v[212:215], v[168:171], 0
	v_mfma_f32_16x16x32_bf16 v[78:81], v[204:207], v[188:191], 0
	v_mfma_f32_16x16x32_bf16 v[74:77], v[212:215], v[188:191], 0
	v_mfma_f32_16x16x32_bf16 v[70:73], v[204:207], v[196:199], 0
	v_mfma_f32_16x16x32_bf16 v[66:69], v[212:215], v[196:199], 0
	v_mfma_f32_16x16x32_bf16 v[110:113], v[208:211], v[164:167], v[110:113]
	v_mfma_f32_16x16x32_bf16 v[102:105], v[216:219], v[164:167], v[102:105]
	v_mfma_f32_16x16x32_bf16 v[94:97], v[208:211], v[172:175], v[94:97]
	v_mfma_f32_16x16x32_bf16 v[86:89], v[216:219], v[172:175], v[86:89]
	v_mfma_f32_16x16x32_bf16 v[78:81], v[208:211], v[192:195], v[78:81]
	v_mfma_f32_16x16x32_bf16 v[74:77], v[216:219], v[192:195], v[74:77]
	v_mfma_f32_16x16x32_bf16 v[70:73], v[208:211], v[200:203], v[70:73]
	v_mfma_f32_16x16x32_bf16 v[66:69], v[216:219], v[200:203], v[66:69]
	s_setprio 0
	s_mov_b32 m0, s89
	v_lshl_add_u64 v[224:225], s[18:19], 0, v[134:135]
	s_barrier
	ds_read_b128 v[160:163], v186 offset:16384
	ds_read_b128 v[164:167], v186 offset:17408
	ds_read_b128 v[168:171], v186 offset:18432
	ds_read_b128 v[172:175], v186 offset:19456
	ds_read_b128 v[188:191], v186 offset:20480
	ds_read_b128 v[192:195], v186 offset:21504
	ds_read_b128 v[196:199], v186 offset:22528
	ds_read_b128 v[200:203], v186 offset:23552
	global_load_lds_dwordx4 v[224:225], off
	v_lshl_add_u64 v[226:227], s[18:19], 0, v[138:139]
	s_mov_b32 m0, s74
	s_nop 0
	global_load_lds_dwordx4 v[226:227], off
	s_barrier
	s_waitcnt lgkmcnt(0)
	s_setprio 1
	s_waitcnt lgkmcnt(0)
	v_mfma_f32_16x16x32_bf16 v[62:65], v[130:133], v[160:163], 0
	v_mfma_f32_16x16x32_bf16 v[58:61], v[152:155], v[160:163], 0
	v_mfma_f32_16x16x32_bf16 v[54:57], v[130:133], v[168:171], 0
	v_mfma_f32_16x16x32_bf16 v[50:53], v[152:155], v[168:171], 0
	v_mfma_f32_16x16x32_bf16 v[46:49], v[130:133], v[188:191], 0
	v_mfma_f32_16x16x32_bf16 v[38:41], v[152:155], v[188:191], 0
	v_mfma_f32_16x16x32_bf16 v[30:33], v[130:133], v[196:199], 0
	v_mfma_f32_16x16x32_bf16 v[22:25], v[152:155], v[196:199], 0
	v_mfma_f32_16x16x32_bf16 v[62:65], v[148:151], v[164:167], v[62:65]
	v_mfma_f32_16x16x32_bf16 v[58:61], v[156:159], v[164:167], v[58:61]
	v_mfma_f32_16x16x32_bf16 v[54:57], v[148:151], v[172:175], v[54:57]
	v_mfma_f32_16x16x32_bf16 v[50:53], v[156:159], v[172:175], v[50:53]
	v_mfma_f32_16x16x32_bf16 v[46:49], v[148:151], v[192:195], v[46:49]
	v_mfma_f32_16x16x32_bf16 v[38:41], v[156:159], v[192:195], v[38:41]
	v_mfma_f32_16x16x32_bf16 v[30:33], v[148:151], v[200:203], v[30:33]
	v_mfma_f32_16x16x32_bf16 v[22:25], v[156:159], v[200:203], v[22:25]
	s_setprio 0
	s_barrier
; #define PG8_STAGE(bufoff, gbase, voff) do { _Pragma("unroll") for (int _i = 0; _i < 2; ++_i) \
;         __builtin_amdgcn_global_load_lds((const unsigned*)((const char*)(gbase) + (voff)[_i]), (LAS unsigned*)(lds + (bufoff) + ldsw + _i * 8192), 16, 0, 0); } while (0)
; #define PG8_LDA(dst, b, h) do { _Pragma("unroll") for (int m = 0; m < 4; ++m) _Pragma("unroll") for (int k = 0; k < 2; ++k) dst[m][k] = *(const LAS bf16x8*)(lds + PG8_SA(b, h) + aoff + m * 2048 + k * 1024); } while (0)
; #define PG8_LDB(dst, b, h) do { _Pragma("unroll") for (int n = 0; n < 2; ++n) _Pragma("unroll") for (int k = 0; k < 2; ++k) dst[n][k] = *(const LAS bf16x8*)(lds + PG8_SB(b, h) + boff + n * 2048 + k * 1024); } while (0)
; #define PG8_MMA(ai, bj, At, Bt) do { __builtin_amdgcn_s_setprio(1); _Pragma("unroll") for (int m = 0; m < 4; ++m) _Pragma("unroll") for (int n = 0; n < 2; ++n) _Pragma("unroll") for (int k = 0; k < 2; ++k) \
;         acc[ai][bj][m][n] = __builtin_amdgcn_mfma_f32_16x16x32_bf16(Bt[n][k], At[m][k], acc[ai][bj][m][n], 0, 0, 0); __builtin_amdgcn_s_setprio(0); } while (0)
; #define PG8_WAIT_V(n) asm volatile("s_waitcnt vmcnt(" #n ")" ::: "memory")
; #define PG8_WAIT_L(n) asm volatile("s_waitcnt lgkmcnt(" #n ")" ::: "memory")
; #define PG8_BAR __builtin_amdgcn_s_barrier()
; #define PG8_SCHED __builtin_amdgcn_sched_barrier(0)
; template <class Epi>
; DI void gemm_phase(LAS unsigned char* lds, const Gemm g, const StaticOrder& S, const Epi& E) {
;     ...
;             PG8_STAGE(PG8_SB(0, 1), b2 + hstepB, voffB);
;             PG8_WAIT_V(6); PG8_BAR; PG8_MMA(1, 1, At, B1); PG8_BAR;
;             PG8_LDB(B0, 1, 0); PG8_SCHED; PG8_LDA(At, 1, 0); PG8_STAGE(PG8_SA(0, 1), a2 + hstepA, voffA);
;             PG8_WAIT_L(8); PG8_BAR; PG8_WAIT_L(0); PG8_MMA(0, 0, At, B0); PG8_BAR; PG8_SCHED;
;             PG8_LDB(B1, 1, 1); PG8_STAGE(PG8_SB(1, 0), b3, voffB);
;             PG8_BAR; PG8_WAIT_L(0); PG8_MMA(0, 1, At, B1); PG8_BAR;
;             PG8_LDA(At, 1, 1); PG8_STAGE(PG8_SA(1, 0), a3, voffA);
	s_add_u32 s42, s42, s98
	s_addc_u32 s43, s43, 0
	s_add_i32 s37, s37, s88
	v_lshl_add_u64 v[228:229], s[42:43], 0, v[136:137]
	s_mov_b32 m0, s37
	v_lshl_add_u64 v[230:231], s[42:43], 0, v[140:141]
	global_load_lds_dwordx4 v[228:229], off
	s_add_i32 m0, s37, 0x2000
	s_nop 0
	global_load_lds_dwordx4 v[230:231], off
	s_waitcnt vmcnt(6)
	s_barrier
	s_setprio 1
	v_mfma_f32_16x16x32_bf16 v[42:45], v[204:207], v[160:163], 0
	v_mfma_f32_16x16x32_bf16 v[34:37], v[212:215], v[160:163], 0
	v_mfma_f32_16x16x32_bf16 v[26:29], v[204:207], v[168:171], 0
	v_mfma_f32_16x16x32_bf16 v[18:21], v[212:215], v[168:171], 0
	v_mfma_f32_16x16x32_bf16 v[14:17], v[204:207], v[188:191], 0
	v_mfma_f32_16x16x32_bf16 v[10:13], v[212:215], v[188:191], 0
	v_mfma_f32_16x16x32_bf16 v[6:9], v[204:207], v[196:199], 0
	v_mfma_f32_16x16x32_bf16 v[2:5], v[212:215], v[196:199], 0
	v_mfma_f32_16x16x32_bf16 v[42:45], v[208:211], v[164:167], v[42:45]
	v_mfma_f32_16x16x32_bf16 v[34:37], v[216:219], v[164:167], v[34:37]
	v_mfma_f32_16x16x32_bf16 v[26:29], v[208:211], v[172:175], v[26:29]
	v_mfma_f32_16x16x32_bf16 v[18:21], v[216:219], v[172:175], v[18:21]
	v_mfma_f32_16x16x32_bf16 v[14:17], v[208:211], v[192:195], v[14:17]
	v_mfma_f32_16x16x32_bf16 v[10:13], v[216:219], v[192:195], v[10:13]
	v_mfma_f32_16x16x32_bf16 v[6:9], v[208:211], v[200:203], v[6:9]
	v_mfma_f32_16x16x32_bf16 v[2:5], v[216:219], v[200:203], v[2:5]
	s_setprio 0
	s_add_i32 s37, 0, 0x18000
	v_add_u32_e32 v0, s37, v147
	s_barrier
	ds_read_b128 v[130:133], v0
	ds_read_b128 v[148:151], v0 offset:1024
	ds_read_b128 v[152:155], v0 offset:2048
	ds_read_b128 v[156:159], v0 offset:3072
	s_add_u32 s18, s18, s72
	s_addc_u32 s19, s19, 0
	s_mov_b32 m0, s75
	v_lshl_add_u64 v[204:205], s[18:19], 0, v[134:135]
	ds_read_b128 v[160:163], v186 offset:32768
	ds_read_b128 v[164:167], v186 offset:33792
	ds_read_b128 v[168:171], v186 offset:34816
	ds_read_b128 v[172:175], v186 offset:35840
	ds_read_b128 v[188:191], v186 offset:36864
	ds_read_b128 v[192:195], v186 offset:37888
	ds_read_b128 v[196:199], v186 offset:38912
	ds_read_b128 v[200:203], v186 offset:39936
	global_load_lds_dwordx4 v[204:205], off
	v_lshl_add_u64 v[204:205], s[18:19], 0, v[138:139]
	s_mov_b32 m0, s3
	s_nop 0
	global_load_lds_dwordx4 v[204:205], off
	s_waitcnt lgkmcnt(8)
	s_barrier
	s_waitcnt lgkmcnt(0)
	s_setprio 1
	s_waitcnt lgkmcnt(0)
	v_mfma_f32_16x16x32_bf16 v[126:129], v[130:133], v[160:163], v[126:129]
	v_mfma_f32_16x16x32_bf16 v[122:125], v[152:155], v[160:163], v[122:125]
	v_mfma_f32_16x16x32_bf16 v[118:121], v[130:133], v[168:171], v[118:121]
	v_mfma_f32_16x16x32_bf16 v[114:117], v[152:155], v[168:171], v[114:117]
	v_mfma_f32_16x16x32_bf16 v[106:109], v[130:133], v[188:191], v[106:109]
	v_mfma_f32_16x16x32_bf16 v[98:101], v[152:155], v[188:191], v[98:101]
	v_mfma_f32_16x16x32_bf16 v[90:93], v[130:133], v[196:199], v[90:93]
	v_mfma_f32_16x16x32_bf16 v[82:85], v[152:155], v[196:199], v[82:85]
	v_mfma_f32_16x16x32_bf16 v[126:129], v[148:151], v[164:167], v[126:129]
	v_mfma_f32_16x16x32_bf16 v[122:125], v[156:159], v[164:167], v[122:125]
	v_mfma_f32_16x16x32_bf16 v[118:121], v[148:151], v[172:175], v[118:121]
	v_mfma_f32_16x16x32_bf16 v[114:117], v[156:159], v[172:175], v[114:117]
	v_mfma_f32_16x16x32_bf16 v[106:109], v[148:151], v[192:195], v[106:109]
	v_mfma_f32_16x16x32_bf16 v[98:101], v[156:159], v[192:195], v[98:101]
	v_mfma_f32_16x16x32_bf16 v[90:93], v[148:151], v[200:203], v[90:93]
	v_mfma_f32_16x16x32_bf16 v[82:85], v[156:159], v[200:203], v[82:85]
	s_setprio 0
	s_barrier
	s_add_i32 s18, 0, 0x1c000
	s_add_i32 s19, s37, s88
	v_add_u32_e32 v0, s18, v147
	v_lshl_add_u64 v[220:221], v[220:221], 0, s[82:83]
	s_mov_b32 m0, s19
	ds_read_b128 v[204:207], v0
	ds_read_b128 v[208:211], v0 offset:1024
	ds_read_b128 v[212:215], v0 offset:2048
	ds_read_b128 v[216:219], v0 offset:3072
	global_load_lds_dwordx4 v[220:221], off
	v_lshl_add_u64 v[220:221], v[222:223], 0, s[82:83]
	s_add_i32 m0, s19, 0x2000
	s_nop 0
	global_load_lds_dwordx4 v[220:221], off
	s_barrier
	s_waitcnt lgkmcnt(0)
	s_setprio 1
	s_waitcnt lgkmcnt(0)
	v_mfma_f32_16x16x32_bf16 v[110:113], v[204:207], v[160:163], v[110:113]
	v_mfma_f32_16x16x32_bf16 v[102:105], v[212:215], v[160:163], v[102:105]
	v_mfma_f32_16x16x32_bf16 v[94:97], v[204:207], v[168:171], v[94:97]
	v_mfma_f32_16x16x32_bf16 v[86:89], v[212:215], v[168:171], v[86:89]
	v_mfma_f32_16x16x32_bf16 v[78:81], v[204:207], v[188:191], v[78:81]
	v_mfma_f32_16x16x32_bf16 v[74:77], v[212:215], v[188:191], v[74:77]
	v_mfma_f32_16x16x32_bf16 v[70:73], v[204:207], v[196:199], v[70:73]
	v_mfma_f32_16x16x32_bf16 v[66:69], v[212:215], v[196:199], v[66:69]
	v_mfma_f32_16x16x32_bf16 v[110:113], v[208:211], v[164:167], v[110:113]
	v_mfma_f32_16x16x32_bf16 v[102:105], v[216:219], v[164:167], v[102:105]
	v_mfma_f32_16x16x32_bf16 v[94:97], v[208:211], v[172:175], v[94:97]
	v_mfma_f32_16x16x32_bf16 v[86:89], v[216:219], v[172:175], v[86:89]
	v_mfma_f32_16x16x32_bf16 v[78:81], v[208:211], v[192:195], v[78:81]
	v_mfma_f32_16x16x32_bf16 v[74:77], v[216:219], v[192:195], v[74:77]
	v_mfma_f32_16x16x32_bf16 v[70:73], v[208:211], v[200:203], v[70:73]
	v_mfma_f32_16x16x32_bf16 v[66:69], v[216:219], v[200:203], v[66:69]
	s_setprio 0
	s_mov_b32 m0, s24
	v_lshl_add_u64 v[220:221], v[224:225], 0, s[82:83]
	s_barrier
	ds_read_b128 v[160:163], v186 offset:49152
	ds_read_b128 v[164:167], v186 offset:50176
	ds_read_b128 v[168:171], v186 offset:51200
	ds_read_b128 v[172:175], v186 offset:52224
	ds_read_b128 v[188:191], v186 offset:53248
	ds_read_b128 v[192:195], v186 offset:54272
	ds_read_b128 v[196:199], v186 offset:55296
	ds_read_b128 v[200:203], v186 offset:56320
	global_load_lds_dwordx4 v[220:221], off
	v_lshl_add_u64 v[220:221], v[226:227], 0, s[82:83]
	s_mov_b32 m0, s97
	s_nop 0
	global_load_lds_dwordx4 v[220:221], off
	s_barrier
; #define PG8_STAGE(bufoff, gbase, voff) do { _Pragma("unroll") for (int _i = 0; _i < 2; ++_i) \
;         __builtin_amdgcn_global_load_lds((const unsigned*)((const char*)(gbase) + (voff)[_i]), (LAS unsigned*)(lds + (bufoff) + ldsw + _i * 8192), 16, 0, 0); } while (0)
; #define PG8_LDA(dst, b, h) do { _Pragma("unroll") for (int m = 0; m < 4; ++m) _Pragma("unroll") for (int k = 0; k < 2; ++k) dst[m][k] = *(const LAS bf16x8*)(lds + PG8_SA(b, h) + aoff + m * 2048 + k * 1024); } while (0)
; #define PG8_LDB(dst, b, h) do { _Pragma("unroll") for (int n = 0; n < 2; ++n) _Pragma("unroll") for (int k = 0; k < 2; ++k) dst[n][k] = *(const LAS bf16x8*)(lds + PG8_SB(b, h) + boff + n * 2048 + k * 1024); } while (0)
; #define PG8_MMA(ai, bj, At, Bt) do { __builtin_amdgcn_s_setprio(1); _Pragma("unroll") for (int m = 0; m < 4; ++m) _Pragma("unroll") for (int n = 0; n < 2; ++n) _Pragma("unroll") for (int k = 0; k < 2; ++k) \
;         acc[ai][bj][m][n] = __builtin_amdgcn_mfma_f32_16x16x32_bf16(Bt[n][k], At[m][k], acc[ai][bj][m][n], 0, 0, 0); __builtin_amdgcn_s_setprio(0); } while (0)
; #define PG8_WAIT_V(n) asm volatile("s_waitcnt vmcnt(" #n ")" ::: "memory")
; #define PG8_WAIT_L(n) asm volatile("s_waitcnt lgkmcnt(" #n ")" ::: "memory")
; #define PG8_BAR __builtin_amdgcn_s_barrier()
; #define PG8_SCHED __builtin_amdgcn_sched_barrier(0)
; template <class Epi>
; DI void gemm_phase(LAS unsigned char* lds, const Gemm g, const StaticOrder& S, const Epi& E) {
;     ...
;             PG8_LDB(B0, 0, 0); PG8_SCHED; PG8_LDA(At, 0, 0); PG8_STAGE(PG8_SA(1, 1), a1 + hstepA, voffA);
;             PG8_WAIT_L(8); PG8_BAR; PG8_WAIT_L(0); PG8_MMA(0, 0, At, B0); PG8_BAR; PG8_SCHED;
;             PG8_LDB(B1, 0, 1); PG8_STAGE(PG8_SB(0, 0), b2, voffB);
;             PG8_BAR; PG8_WAIT_L(0); PG8_MMA(0, 1, At, B1); PG8_BAR;
;             PG8_LDA(At, 0, 1); PG8_STAGE(PG8_SA(0, 0), a2, voffA);
;     ...
;             PG8_BAR; PG8_WAIT_L(0); PG8_MMA(1, 0, At, B0); PG8_BAR; PG8_SCHED;
;             PG8_STAGE(PG8_SB(1, 1), b3 + hstepB, voffB);
;             PG8_WAIT_V(6); PG8_BAR; PG8_MMA(1, 1, At, B1); PG8_BAR;
;         }
	s_waitcnt lgkmcnt(0)
	s_setprio 1
	s_waitcnt lgkmcnt(0)
	v_mfma_f32_16x16x32_bf16 v[62:65], v[130:133], v[160:163], v[62:65]
	v_mfma_f32_16x16x32_bf16 v[58:61], v[152:155], v[160:163], v[58:61]
	v_mfma_f32_16x16x32_bf16 v[54:57], v[130:133], v[168:171], v[54:57]
	v_mfma_f32_16x16x32_bf16 v[50:53], v[152:155], v[168:171], v[50:53]
	v_mfma_f32_16x16x32_bf16 v[46:49], v[130:133], v[188:191], v[46:49]
	v_mfma_f32_16x16x32_bf16 v[38:41], v[152:155], v[188:191], v[38:41]
	v_mfma_f32_16x16x32_bf16 v[30:33], v[130:133], v[196:199], v[30:33]
	v_mfma_f32_16x16x32_bf16 v[22:25], v[152:155], v[196:199], v[22:25]
	v_mfma_f32_16x16x32_bf16 v[62:65], v[148:151], v[164:167], v[62:65]
	v_mfma_f32_16x16x32_bf16 v[58:61], v[156:159], v[164:167], v[58:61]
	v_mfma_f32_16x16x32_bf16 v[54:57], v[148:151], v[172:175], v[54:57]
	v_mfma_f32_16x16x32_bf16 v[50:53], v[156:159], v[172:175], v[50:53]
	v_mfma_f32_16x16x32_bf16 v[46:49], v[148:151], v[192:195], v[46:49]
	v_mfma_f32_16x16x32_bf16 v[38:41], v[156:159], v[192:195], v[38:41]
	v_mfma_f32_16x16x32_bf16 v[30:33], v[148:151], v[200:203], v[30:33]
	v_mfma_f32_16x16x32_bf16 v[22:25], v[156:159], v[200:203], v[22:25]
	s_setprio 0
	s_barrier
	s_add_i32 s18, s18, s88
	v_lshl_add_u64 v[130:131], v[228:229], 0, s[82:83]
	s_mov_b32 m0, s18
	s_nop 0
	global_load_lds_dwordx4 v[130:131], off
	v_lshl_add_u64 v[130:131], v[230:231], 0, s[82:83]
	s_add_i32 m0, s18, 0x2000
	s_nop 0
	global_load_lds_dwordx4 v[130:131], off
	s_waitcnt vmcnt(6)
	s_barrier
	s_setprio 1
	v_mfma_f32_16x16x32_bf16 v[42:45], v[204:207], v[160:163], v[42:45]
	v_mfma_f32_16x16x32_bf16 v[34:37], v[212:215], v[160:163], v[34:37]
	v_mfma_f32_16x16x32_bf16 v[26:29], v[204:207], v[168:171], v[26:29]
	v_mfma_f32_16x16x32_bf16 v[18:21], v[212:215], v[168:171], v[18:21]
	v_mfma_f32_16x16x32_bf16 v[14:17], v[204:207], v[188:191], v[14:17]
	v_mfma_f32_16x16x32_bf16 v[10:13], v[212:215], v[188:191], v[10:13]
	v_mfma_f32_16x16x32_bf16 v[6:9], v[204:207], v[196:199], v[6:9]
	v_mfma_f32_16x16x32_bf16 v[2:5], v[212:215], v[196:199], v[2:5]
	v_mfma_f32_16x16x32_bf16 v[42:45], v[208:211], v[164:167], v[42:45]
	v_mfma_f32_16x16x32_bf16 v[34:37], v[216:219], v[164:167], v[34:37]
	v_mfma_f32_16x16x32_bf16 v[26:29], v[208:211], v[172:175], v[26:29]
	v_mfma_f32_16x16x32_bf16 v[18:21], v[216:219], v[172:175], v[18:21]
	v_mfma_f32_16x16x32_bf16 v[14:17], v[208:211], v[192:195], v[14:17]
	v_mfma_f32_16x16x32_bf16 v[10:13], v[216:219], v[192:195], v[10:13]
	v_mfma_f32_16x16x32_bf16 v[6:9], v[208:211], v[200:203], v[6:9]
	v_mfma_f32_16x16x32_bf16 v[2:5], v[216:219], v[200:203], v[2:5]
	s_setprio 0
	s_add_u32 s21, s21, 0x100
	s_addc_u32 s44, s44, 0
	s_add_u32 s16, s16, 0x100
	s_addc_u32 s17, s17, 0
	s_add_u32 s37, s16, 0x80
	s_addc_u32 s19, s17, 0
	s_add_i32 s46, 0, 0x10000
	v_add_u32_e32 v0, s46, v147
	s_cmp_ge_u32 s45, s11
	s_mov_b32 s18, s45
	s_barrier
	s_cbranch_scc1 .Lk_loop_exit
	s_nop 0
	s_nop 0
	s_nop 0
	s_nop 0
	s_nop 0
	s_nop 0
	s_nop 0
	s_nop 0
	s_nop 0
	s_nop 0
.LBB0_241:
	s_add_i32 s45, s18, 2
	s_waitcnt lgkmcnt(0)
	ds_read_b128 v[130:133], v0
	ds_read_b128 v[148:151], v0 offset:1024
	ds_read_b128 v[152:155], v0 offset:2048
	ds_read_b128 v[156:159], v0 offset:3072
	s_cmp_eq_u32 s20, s18
	s_cselect_b32 s18, s12, s37
	s_cselect_b32 s19, s13, s19
	s_cselect_b32 s43, s15, s44
	s_cselect_b32 s42, s14, s21
	v_lshl_add_u64 v[204:205], s[16:17], 0, v[144:145]
	s_add_i32 m0, s89, 0xc000
	ds_read_b128 v[160:163], v186
	ds_read_b128 v[164:167], v186 offset:1024
	ds_read_b128 v[168:171], v186 offset:2048
	ds_read_b128 v[172:175], v186 offset:3072
	ds_read_b128 v[188:191], v186 offset:4096
	ds_read_b128 v[192:195], v186 offset:5120
	ds_read_b128 v[196:199], v186 offset:6144
	ds_read_b128 v[200:203], v186 offset:7168
	global_load_lds_dwordx4 v[204:205], off
	v_lshl_add_u64 v[204:205], s[16:17], 0, v[142:143]
	s_add_i32 m0, s89, 0xe000
	s_nop 0
	global_load_lds_dwordx4 v[204:205], off
	s_waitcnt lgkmcnt(8)
	s_barrier
	s_waitcnt lgkmcnt(0)
	s_setprio 1
	s_waitcnt lgkmcnt(0)
	v_mfma_f32_16x16x32_bf16 v[126:129], v[130:133], v[160:163], v[126:129]
	v_mfma_f32_16x16x32_bf16 v[122:125], v[152:155], v[160:163], v[122:125]
	v_mfma_f32_16x16x32_bf16 v[118:121], v[130:133], v[168:171], v[118:121]
	v_mfma_f32_16x16x32_bf16 v[114:117], v[152:155], v[168:171], v[114:117]
	v_mfma_f32_16x16x32_bf16 v[106:109], v[130:133], v[188:191], v[106:109]
	v_mfma_f32_16x16x32_bf16 v[98:101], v[152:155], v[188:191], v[98:101]
	v_mfma_f32_16x16x32_bf16 v[90:93], v[130:133], v[196:199], v[90:93]
	v_mfma_f32_16x16x32_bf16 v[82:85], v[152:155], v[196:199], v[82:85]
	v_mfma_f32_16x16x32_bf16 v[126:129], v[148:151], v[164:167], v[126:129]
	v_mfma_f32_16x16x32_bf16 v[122:125], v[156:159], v[164:167], v[122:125]
	v_mfma_f32_16x16x32_bf16 v[118:121], v[148:151], v[172:175], v[118:121]
	v_mfma_f32_16x16x32_bf16 v[114:117], v[156:159], v[172:175], v[114:117]
	v_mfma_f32_16x16x32_bf16 v[106:109], v[148:151], v[192:195], v[106:109]
	v_mfma_f32_16x16x32_bf16 v[98:101], v[156:159], v[192:195], v[98:101]
	v_mfma_f32_16x16x32_bf16 v[90:93], v[148:151], v[200:203], v[90:93]
	v_mfma_f32_16x16x32_bf16 v[82:85], v[156:159], v[200:203], v[82:85]
	s_setprio 0
	s_barrier
	s_add_i32 s37, 0, 0x14000
	s_add_i32 s46, s46, s88
	v_add_u32_e32 v0, s37, v147
	v_lshl_add_u64 v[220:221], s[42:43], 0, v[136:137]
	s_mov_b32 m0, s46
	ds_read_b128 v[204:207], v0
	ds_read_b128 v[208:211], v0 offset:1024
	ds_read_b128 v[212:215], v0 offset:2048
	ds_read_b128 v[216:219], v0 offset:3072
	global_load_lds_dwordx4 v[220:221], off
	v_lshl_add_u64 v[222:223], s[42:43], 0, v[140:141]
	s_add_i32 m0, s46, 0x2000
	s_nop 0
	global_load_lds_dwordx4 v[222:223], off
	s_barrier
; #define PG8_STAGE(bufoff, gbase, voff) do { _Pragma("unroll") for (int _i = 0; _i < 2; ++_i) \
;         __builtin_amdgcn_global_load_lds((const unsigned*)((const char*)(gbase) + (voff)[_i]), (LAS unsigned*)(lds + (bufoff) + ldsw + _i * 8192), 16, 0, 0); } while (0)
; #define PG8_LDA(dst, b, h) do { _Pragma("unroll") for (int m = 0; m < 4; ++m) _Pragma("unroll") for (int k = 0; k < 2; ++k) dst[m][k] = *(const LAS bf16x8*)(lds + PG8_SA(b, h) + aoff + m * 2048 + k * 1024); } while (0)
; #define PG8_LDB(dst, b, h) do { _Pragma("unroll") for (int n = 0; n < 2; ++n) _Pragma("unroll") for (int k = 0; k < 2; ++k) dst[n][k] = *(const LAS bf16x8*)(lds + PG8_SB(b, h) + boff + n * 2048 + k * 1024); } while (0)
; #define PG8_MMA(ai, bj, At, Bt) do { __builtin_amdgcn_s_setprio(1); _Pragma("unroll") for (int m = 0; m < 4; ++m) _Pragma("unroll") for (int n = 0; n < 2; ++n) _Pragma("unroll") for (int k = 0; k < 2; ++k) \
;         acc[ai][bj][m][n] = __builtin_amdgcn_mfma_f32_16x16x32_bf16(Bt[n][k], At[m][k], acc[ai][bj][m][n], 0, 0, 0); __builtin_amdgcn_s_setprio(0); } while (0)
; #define PG8_WAIT_V(n) asm volatile("s_waitcnt vmcnt(" #n ")" ::: "memory")
; #define PG8_WAIT_L(n) asm volatile("s_waitcnt lgkmcnt(" #n ")" ::: "memory")
; #define PG8_BAR __builtin_amdgcn_s_barrier()
; #define PG8_SCHED __builtin_amdgcn_sched_barrier(0)
; template <class Epi>
; DI void gemm_phase(LAS unsigned char* lds, const Gemm g, const StaticOrder& S, const Epi& E) {
;     ...
;             PG8_BAR; PG8_WAIT_L(0); PG8_MMA(0, 1, At, B1); PG8_BAR;
;             PG8_LDA(At, 0, 1); PG8_STAGE(PG8_SA(0, 0), a2, voffA);
;             PG8_BAR; PG8_WAIT_L(0); PG8_MMA(1, 0, At, B0); PG8_BAR; PG8_SCHED;
;             PG8_STAGE(PG8_SB(0, 1), b2 + hstepB, voffB);
;             PG8_WAIT_V(6); PG8_BAR; PG8_MMA(1, 1, At, B1); PG8_BAR;
;             PG8_LDB(B0, 1, 0); PG8_SCHED; PG8_LDA(At, 1, 0); PG8_STAGE(PG8_SA(0, 1), a2 + hstepA, voffA);
;             PG8_WAIT_L(8); PG8_BAR; PG8_WAIT_L(0); PG8_MMA(0, 0, At, B0); PG8_BAR; PG8_SCHED;
	s_waitcnt lgkmcnt(0)
	s_setprio 1
	s_waitcnt lgkmcnt(0)
	v_mfma_f32_16x16x32_bf16 v[110:113], v[204:207], v[160:163], v[110:113]
	v_mfma_f32_16x16x32_bf16 v[102:105], v[212:215], v[160:163], v[102:105]
	v_mfma_f32_16x16x32_bf16 v[94:97], v[204:207], v[168:171], v[94:97]
	v_mfma_f32_16x16x32_bf16 v[86:89], v[212:215], v[168:171], v[86:89]
	v_mfma_f32_16x16x32_bf16 v[78:81], v[204:207], v[188:191], v[78:81]
	v_mfma_f32_16x16x32_bf16 v[74:77], v[212:215], v[188:191], v[74:77]
	v_mfma_f32_16x16x32_bf16 v[70:73], v[204:207], v[196:199], v[70:73]
	v_mfma_f32_16x16x32_bf16 v[66:69], v[212:215], v[196:199], v[66:69]
	v_mfma_f32_16x16x32_bf16 v[110:113], v[208:211], v[164:167], v[110:113]
	v_mfma_f32_16x16x32_bf16 v[102:105], v[216:219], v[164:167], v[102:105]
	v_mfma_f32_16x16x32_bf16 v[94:97], v[208:211], v[172:175], v[94:97]
	v_mfma_f32_16x16x32_bf16 v[86:89], v[216:219], v[172:175], v[86:89]
	v_mfma_f32_16x16x32_bf16 v[78:81], v[208:211], v[192:195], v[78:81]
	v_mfma_f32_16x16x32_bf16 v[74:77], v[216:219], v[192:195], v[74:77]
	v_mfma_f32_16x16x32_bf16 v[70:73], v[208:211], v[200:203], v[70:73]
	v_mfma_f32_16x16x32_bf16 v[66:69], v[216:219], v[200:203], v[66:69]
	s_setprio 0
	s_mov_b32 m0, s89
	v_lshl_add_u64 v[224:225], s[18:19], 0, v[134:135]
	s_barrier
	ds_read_b128 v[160:163], v186 offset:16384
	ds_read_b128 v[164:167], v186 offset:17408
	ds_read_b128 v[168:171], v186 offset:18432
	ds_read_b128 v[172:175], v186 offset:19456
	ds_read_b128 v[188:191], v186 offset:20480
	ds_read_b128 v[192:195], v186 offset:21504
	ds_read_b128 v[196:199], v186 offset:22528
	ds_read_b128 v[200:203], v186 offset:23552
	global_load_lds_dwordx4 v[224:225], off
	v_lshl_add_u64 v[226:227], s[18:19], 0, v[138:139]
	s_mov_b32 m0, s74
	s_nop 0
	global_load_lds_dwordx4 v[226:227], off
	s_barrier
	s_waitcnt lgkmcnt(0)
	s_setprio 1
	s_waitcnt lgkmcnt(0)
	v_mfma_f32_16x16x32_bf16 v[62:65], v[130:133], v[160:163], v[62:65]
	v_mfma_f32_16x16x32_bf16 v[58:61], v[152:155], v[160:163], v[58:61]
	v_mfma_f32_16x16x32_bf16 v[54:57], v[130:133], v[168:171], v[54:57]
	v_mfma_f32_16x16x32_bf16 v[50:53], v[152:155], v[168:171], v[50:53]
	v_mfma_f32_16x16x32_bf16 v[46:49], v[130:133], v[188:191], v[46:49]
	v_mfma_f32_16x16x32_bf16 v[38:41], v[152:155], v[188:191], v[38:41]
	v_mfma_f32_16x16x32_bf16 v[30:33], v[130:133], v[196:199], v[30:33]
	v_mfma_f32_16x16x32_bf16 v[22:25], v[152:155], v[196:199], v[22:25]
	v_mfma_f32_16x16x32_bf16 v[62:65], v[148:151], v[164:167], v[62:65]
	v_mfma_f32_16x16x32_bf16 v[58:61], v[156:159], v[164:167], v[58:61]
	v_mfma_f32_16x16x32_bf16 v[54:57], v[148:151], v[172:175], v[54:57]
	v_mfma_f32_16x16x32_bf16 v[50:53], v[156:159], v[172:175], v[50:53]
	v_mfma_f32_16x16x32_bf16 v[46:49], v[148:151], v[192:195], v[46:49]
	v_mfma_f32_16x16x32_bf16 v[38:41], v[156:159], v[192:195], v[38:41]
	v_mfma_f32_16x16x32_bf16 v[30:33], v[148:151], v[200:203], v[30:33]
	v_mfma_f32_16x16x32_bf16 v[22:25], v[156:159], v[200:203], v[22:25]
	s_setprio 0
	s_barrier
	s_add_u32 s42, s42, s98
	s_addc_u32 s43, s43, 0
	s_add_i32 s37, s37, s88
	v_lshl_add_u64 v[228:229], s[42:43], 0, v[136:137]
	s_mov_b32 m0, s37
	v_lshl_add_u64 v[230:231], s[42:43], 0, v[140:141]
	global_load_lds_dwordx4 v[228:229], off
	s_add_i32 m0, s37, 0x2000
	s_nop 0
	global_load_lds_dwordx4 v[230:231], off
	s_waitcnt vmcnt(6)
	s_barrier
	s_setprio 1
	v_mfma_f32_16x16x32_bf16 v[42:45], v[204:207], v[160:163], v[42:45]
	v_mfma_f32_16x16x32_bf16 v[34:37], v[212:215], v[160:163], v[34:37]
	v_mfma_f32_16x16x32_bf16 v[26:29], v[204:207], v[168:171], v[26:29]
	v_mfma_f32_16x16x32_bf16 v[18:21], v[212:215], v[168:171], v[18:21]
	v_mfma_f32_16x16x32_bf16 v[14:17], v[204:207], v[188:191], v[14:17]
	v_mfma_f32_16x16x32_bf16 v[10:13], v[212:215], v[188:191], v[10:13]
	v_mfma_f32_16x16x32_bf16 v[6:9], v[204:207], v[196:199], v[6:9]
	v_mfma_f32_16x16x32_bf16 v[2:5], v[212:215], v[196:199], v[2:5]
	v_mfma_f32_16x16x32_bf16 v[42:45], v[208:211], v[164:167], v[42:45]
	v_mfma_f32_16x16x32_bf16 v[34:37], v[216:219], v[164:167], v[34:37]
	v_mfma_f32_16x16x32_bf16 v[26:29], v[208:211], v[172:175], v[26:29]
	v_mfma_f32_16x16x32_bf16 v[18:21], v[216:219], v[172:175], v[18:21]
	v_mfma_f32_16x16x32_bf16 v[14:17], v[208:211], v[192:195], v[14:17]
	v_mfma_f32_16x16x32_bf16 v[10:13], v[216:219], v[192:195], v[10:13]
	v_mfma_f32_16x16x32_bf16 v[6:9], v[208:211], v[200:203], v[6:9]
	v_mfma_f32_16x16x32_bf16 v[2:5], v[216:219], v[200:203], v[2:5]
	s_setprio 0
	s_add_i32 s37, 0, 0x18000
	v_add_u32_e32 v0, s37, v147
	s_barrier
	ds_read_b128 v[130:133], v0
	ds_read_b128 v[148:151], v0 offset:1024
	ds_read_b128 v[152:155], v0 offset:2048
	ds_read_b128 v[156:159], v0 offset:3072
	s_add_u32 s18, s18, s72
	s_addc_u32 s19, s19, 0
	s_mov_b32 m0, s75
	v_lshl_add_u64 v[204:205], s[18:19], 0, v[134:135]
	ds_read_b128 v[160:163], v186 offset:32768
	ds_read_b128 v[164:167], v186 offset:33792
	ds_read_b128 v[168:171], v186 offset:34816
	ds_read_b128 v[172:175], v186 offset:35840
	ds_read_b128 v[188:191], v186 offset:36864
	ds_read_b128 v[192:195], v186 offset:37888
	ds_read_b128 v[196:199], v186 offset:38912
	ds_read_b128 v[200:203], v186 offset:39936
	global_load_lds_dwordx4 v[204:205], off
	v_lshl_add_u64 v[204:205], s[18:19], 0, v[138:139]
	s_mov_b32 m0, s3
	s_nop 0
	global_load_lds_dwordx4 v[204:205], off
	s_waitcnt lgkmcnt(8)
	s_barrier
; #define PG8_STAGE(bufoff, gbase, voff) do { _Pragma("unroll") for (int _i = 0; _i < 2; ++_i) \
;         __builtin_amdgcn_global_load_lds((const unsigned*)((const char*)(gbase) + (voff)[_i]), (LAS unsigned*)(lds + (bufoff) + ldsw + _i * 8192), 16, 0, 0); } while (0)
; #define PG8_LDA(dst, b, h) do { _Pragma("unroll") for (int m = 0; m < 4; ++m) _Pragma("unroll") for (int k = 0; k < 2; ++k) dst[m][k] = *(const LAS bf16x8*)(lds + PG8_SA(b, h) + aoff + m * 2048 + k * 1024); } while (0)
; #define PG8_LDB(dst, b, h) do { _Pragma("unroll") for (int n = 0; n < 2; ++n) _Pragma("unroll") for (int k = 0; k < 2; ++k) dst[n][k] = *(const LAS bf16x8*)(lds + PG8_SB(b, h) + boff + n * 2048 + k * 1024); } while (0)
; #define PG8_MMA(ai, bj, At, Bt) do { __builtin_amdgcn_s_setprio(1); _Pragma("unroll") for (int m = 0; m < 4; ++m) _Pragma("unroll") for (int n = 0; n < 2; ++n) _Pragma("unroll") for (int k = 0; k < 2; ++k) \
;         acc[ai][bj][m][n] = __builtin_amdgcn_mfma_f32_16x16x32_bf16(Bt[n][k], At[m][k], acc[ai][bj][m][n], 0, 0, 0); __builtin_amdgcn_s_setprio(0); } while (0)
; #define PG8_WAIT_V(n) asm volatile("s_waitcnt vmcnt(" #n ")" ::: "memory")
; #define PG8_WAIT_L(n) asm volatile("s_waitcnt lgkmcnt(" #n ")" ::: "memory")
; #define PG8_BAR __builtin_amdgcn_s_barrier()
; #define PG8_SCHED __builtin_amdgcn_sched_barrier(0)
; template <class Epi>
; DI void gemm_phase(LAS unsigned char* lds, const Gemm g, const StaticOrder& S, const Epi& E) {
;     ...
;         for (int t = 0; t < ntc; t += 2) {
;     ...
;             PG8_WAIT_L(8); PG8_BAR; PG8_WAIT_L(0); PG8_MMA(0, 0, At, B0); PG8_BAR; PG8_SCHED;
;             PG8_LDB(B1, 1, 1); PG8_STAGE(PG8_SB(1, 0), b3, voffB);
;             PG8_BAR; PG8_WAIT_L(0); PG8_MMA(0, 1, At, B1); PG8_BAR;
;             PG8_LDA(At, 1, 1); PG8_STAGE(PG8_SA(1, 0), a3, voffA);
;             PG8_BAR; PG8_WAIT_L(0); PG8_MMA(1, 0, At, B0); PG8_BAR; PG8_SCHED;
;             PG8_STAGE(PG8_SB(1, 1), b3 + hstepB, voffB);
;             PG8_WAIT_V(6); PG8_BAR; PG8_MMA(1, 1, At, B1); PG8_BAR;
	s_waitcnt lgkmcnt(0)
	s_setprio 1
	s_waitcnt lgkmcnt(0)
	v_mfma_f32_16x16x32_bf16 v[126:129], v[130:133], v[160:163], v[126:129]
	v_mfma_f32_16x16x32_bf16 v[122:125], v[152:155], v[160:163], v[122:125]
	v_mfma_f32_16x16x32_bf16 v[118:121], v[130:133], v[168:171], v[118:121]
	v_mfma_f32_16x16x32_bf16 v[114:117], v[152:155], v[168:171], v[114:117]
	v_mfma_f32_16x16x32_bf16 v[106:109], v[130:133], v[188:191], v[106:109]
	v_mfma_f32_16x16x32_bf16 v[98:101], v[152:155], v[188:191], v[98:101]
	v_mfma_f32_16x16x32_bf16 v[90:93], v[130:133], v[196:199], v[90:93]
	v_mfma_f32_16x16x32_bf16 v[82:85], v[152:155], v[196:199], v[82:85]
	v_mfma_f32_16x16x32_bf16 v[126:129], v[148:151], v[164:167], v[126:129]
	v_mfma_f32_16x16x32_bf16 v[122:125], v[156:159], v[164:167], v[122:125]
	v_mfma_f32_16x16x32_bf16 v[118:121], v[148:151], v[172:175], v[118:121]
	v_mfma_f32_16x16x32_bf16 v[114:117], v[156:159], v[172:175], v[114:117]
	v_mfma_f32_16x16x32_bf16 v[106:109], v[148:151], v[192:195], v[106:109]
	v_mfma_f32_16x16x32_bf16 v[98:101], v[156:159], v[192:195], v[98:101]
	v_mfma_f32_16x16x32_bf16 v[90:93], v[148:151], v[200:203], v[90:93]
	v_mfma_f32_16x16x32_bf16 v[82:85], v[156:159], v[200:203], v[82:85]
	s_setprio 0
	s_barrier
	s_add_i32 s18, 0, 0x1c000
	s_add_i32 s19, s37, s88
	v_add_u32_e32 v0, s18, v147
	v_lshl_add_u64 v[220:221], v[220:221], 0, s[82:83]
	s_mov_b32 m0, s19
	ds_read_b128 v[204:207], v0
	ds_read_b128 v[208:211], v0 offset:1024
	ds_read_b128 v[212:215], v0 offset:2048
	ds_read_b128 v[216:219], v0 offset:3072
	global_load_lds_dwordx4 v[220:221], off
	v_lshl_add_u64 v[220:221], v[222:223], 0, s[82:83]
	s_add_i32 m0, s19, 0x2000
	s_nop 0
	global_load_lds_dwordx4 v[220:221], off
	s_barrier
	s_waitcnt lgkmcnt(0)
	s_setprio 1
	s_waitcnt lgkmcnt(0)
	v_mfma_f32_16x16x32_bf16 v[110:113], v[204:207], v[160:163], v[110:113]
	v_mfma_f32_16x16x32_bf16 v[102:105], v[212:215], v[160:163], v[102:105]
	v_mfma_f32_16x16x32_bf16 v[94:97], v[204:207], v[168:171], v[94:97]
	v_mfma_f32_16x16x32_bf16 v[86:89], v[212:215], v[168:171], v[86:89]
	v_mfma_f32_16x16x32_bf16 v[78:81], v[204:207], v[188:191], v[78:81]
	v_mfma_f32_16x16x32_bf16 v[74:77], v[212:215], v[188:191], v[74:77]
	v_mfma_f32_16x16x32_bf16 v[70:73], v[204:207], v[196:199], v[70:73]
	v_mfma_f32_16x16x32_bf16 v[66:69], v[212:215], v[196:199], v[66:69]
	v_mfma_f32_16x16x32_bf16 v[110:113], v[208:211], v[164:167], v[110:113]
	v_mfma_f32_16x16x32_bf16 v[102:105], v[216:219], v[164:167], v[102:105]
	v_mfma_f32_16x16x32_bf16 v[94:97], v[208:211], v[172:175], v[94:97]
	v_mfma_f32_16x16x32_bf16 v[86:89], v[216:219], v[172:175], v[86:89]
	v_mfma_f32_16x16x32_bf16 v[78:81], v[208:211], v[192:195], v[78:81]
	v_mfma_f32_16x16x32_bf16 v[74:77], v[216:219], v[192:195], v[74:77]
	v_mfma_f32_16x16x32_bf16 v[70:73], v[208:211], v[200:203], v[70:73]
	v_mfma_f32_16x16x32_bf16 v[66:69], v[216:219], v[200:203], v[66:69]
	s_setprio 0
	s_mov_b32 m0, s24
	v_lshl_add_u64 v[220:221], v[224:225], 0, s[82:83]
	s_barrier
	ds_read_b128 v[160:163], v186 offset:49152
	ds_read_b128 v[164:167], v186 offset:50176
	ds_read_b128 v[168:171], v186 offset:51200
	ds_read_b128 v[172:175], v186 offset:52224
	ds_read_b128 v[188:191], v186 offset:53248
	ds_read_b128 v[192:195], v186 offset:54272
	ds_read_b128 v[196:199], v186 offset:55296
	ds_read_b128 v[200:203], v186 offset:56320
	global_load_lds_dwordx4 v[220:221], off
	v_lshl_add_u64 v[220:221], v[226:227], 0, s[82:83]
	s_mov_b32 m0, s97
	s_nop 0
	global_load_lds_dwordx4 v[220:221], off
	s_barrier
	s_waitcnt lgkmcnt(0)
	s_setprio 1
	s_waitcnt lgkmcnt(0)
	v_mfma_f32_16x16x32_bf16 v[62:65], v[130:133], v[160:163], v[62:65]
	v_mfma_f32_16x16x32_bf16 v[58:61], v[152:155], v[160:163], v[58:61]
	v_mfma_f32_16x16x32_bf16 v[54:57], v[130:133], v[168:171], v[54:57]
	v_mfma_f32_16x16x32_bf16 v[50:53], v[152:155], v[168:171], v[50:53]
	v_mfma_f32_16x16x32_bf16 v[46:49], v[130:133], v[188:191], v[46:49]
	v_mfma_f32_16x16x32_bf16 v[38:41], v[152:155], v[188:191], v[38:41]
	v_mfma_f32_16x16x32_bf16 v[30:33], v[130:133], v[196:199], v[30:33]
	v_mfma_f32_16x16x32_bf16 v[22:25], v[152:155], v[196:199], v[22:25]
	v_mfma_f32_16x16x32_bf16 v[62:65], v[148:151], v[164:167], v[62:65]
	v_mfma_f32_16x16x32_bf16 v[58:61], v[156:159], v[164:167], v[58:61]
	v_mfma_f32_16x16x32_bf16 v[54:57], v[148:151], v[172:175], v[54:57]
	v_mfma_f32_16x16x32_bf16 v[50:53], v[156:159], v[172:175], v[50:53]
	v_mfma_f32_16x16x32_bf16 v[46:49], v[148:151], v[192:195], v[46:49]
	v_mfma_f32_16x16x32_bf16 v[38:41], v[156:159], v[192:195], v[38:41]
	v_mfma_f32_16x16x32_bf16 v[30:33], v[148:151], v[200:203], v[30:33]
	v_mfma_f32_16x16x32_bf16 v[22:25], v[156:159], v[200:203], v[22:25]
	s_setprio 0
	s_barrier
	s_add_i32 s18, s18, s88
	v_lshl_add_u64 v[130:131], v[228:229], 0, s[82:83]
	s_mov_b32 m0, s18
	s_nop 0
	global_load_lds_dwordx4 v[130:131], off
	v_lshl_add_u64 v[130:131], v[230:231], 0, s[82:83]
	s_add_i32 m0, s18, 0x2000
	s_nop 0
	global_load_lds_dwordx4 v[130:131], off
	s_waitcnt vmcnt(6)
	s_barrier
	s_setprio 1
	v_mfma_f32_16x16x32_bf16 v[42:45], v[204:207], v[160:163], v[42:45]
	v_mfma_f32_16x16x32_bf16 v[34:37], v[212:215], v[160:163], v[34:37]
	v_mfma_f32_16x16x32_bf16 v[26:29], v[204:207], v[168:171], v[26:29]
	v_mfma_f32_16x16x32_bf16 v[18:21], v[212:215], v[168:171], v[18:21]
	v_mfma_f32_16x16x32_bf16 v[14:17], v[204:207], v[188:191], v[14:17]
	v_mfma_f32_16x16x32_bf16 v[10:13], v[212:215], v[188:191], v[10:13]
	v_mfma_f32_16x16x32_bf16 v[6:9], v[204:207], v[196:199], v[6:9]
	v_mfma_f32_16x16x32_bf16 v[2:5], v[212:215], v[196:199], v[2:5]
	v_mfma_f32_16x16x32_bf16 v[42:45], v[208:211], v[164:167], v[42:45]
	v_mfma_f32_16x16x32_bf16 v[34:37], v[216:219], v[164:167], v[34:37]
	v_mfma_f32_16x16x32_bf16 v[26:29], v[208:211], v[172:175], v[26:29]
	v_mfma_f32_16x16x32_bf16 v[18:21], v[216:219], v[172:175], v[18:21]
	v_mfma_f32_16x16x32_bf16 v[14:17], v[208:211], v[192:195], v[14:17]
	v_mfma_f32_16x16x32_bf16 v[10:13], v[216:219], v[192:195], v[10:13]
	v_mfma_f32_16x16x32_bf16 v[6:9], v[208:211], v[200:203], v[6:9]
	v_mfma_f32_16x16x32_bf16 v[2:5], v[216:219], v[200:203], v[2:5]
	s_setprio 0
	s_add_u32 s21, s21, 0x100
	s_addc_u32 s44, s44, 0
	s_add_u32 s16, s16, 0x100
	s_addc_u32 s17, s17, 0
	s_add_u32 s37, s16, 0x80
	s_addc_u32 s19, s17, 0
	s_add_i32 s46, 0, 0x10000
	v_add_u32_e32 v0, s46, v147
	s_cmp_ge_u32 s45, s11
	s_mov_b32 s18, s45
	s_barrier
	s_cbranch_scc0 .LBB0_241
